# gating mixer (SGU) quarter loop: the 8 u-tile loads issued at the top of each quarter behind the v-tile loads (into otherwise idle registers), v wait becomes vmcnt(9): one exposed memory latency per q
# baseline (speedup 1.0000x reference)
; #define LAS __attribute__((address_space(3)))
; __device__ __forceinline__ unsigned pk2(float lo, float hi) { return f2bf(lo) | (f2bf(hi) << 16); }
; __device__ __forceinline__ float bflo(unsigned w) { return __uint_as_float(w << 16); }
; __device__ __forceinline__ float bfhi(unsigned w) { return __uint_as_float(w & 0xffff0000u); }
; __device__ __forceinline__ void sgu_item(LAS unsigned char* wl, const bf16* proj, bf16* ymix, const float* vstat, const float* sgu_g, const bf16* Wm, const float* sgu_b, int chunk, int h, int lane) {
;     ...
;     for (int dq = 0; dq < 4; ++dq) {
;         const int colv = h * 128 + dq * 32;
;         v4u raw[8];
; #pragma unroll
;         for (int i = 0; i < 8; ++i) raw[i] = __builtin_nontemporal_load((const v4u*)(proj + (R0 + rsub + 16 * i) * DIN + 1024 + colv + c16 * 8));
;         const f32x4 g0 = *(const f32x4*)(sgu_g + colv + c16 * 8), g1 = *(const f32x4*)(sgu_g + colv + c16 * 8 + 4);
; #pragma unroll
;         for (int i = 0; i < 8; ++i) { const int s = rsub + 16 * i; const f32x2 ms = st[s]; const v4u w = raw[i];
;             v2u lo, hi; lo.x = pk2((bflo(w.x) - ms.x) * ms.y * g0[0], (bfhi(w.x) - ms.x) * ms.y * g0[1]); lo.y = pk2((bflo(w.y) - ms.x) * ms.y * g0[2], (bfhi(w.y) - ms.x) * ms.y * g0[3]);
;             hi.x = pk2((bflo(w.z) - ms.x) * ms.y * g1[0], (bfhi(w.z) - ms.x) * ms.y * g1[1]); hi.y = pk2((bflo(w.w) - ms.x) * ms.y * g1[2], (bfhi(w.w) - ms.x) * ms.y * g1[3]);
;             *(LAS v2u*)(wl + s * VP2 + (4 * c16) * 2) = lo; *(LAS v2u*)(wl + s * VP2 + (16 + 4 * c16) * 2) = hi; }
;         v4u uu8[8];
; #pragma unroll
;         for (int tb = 0; tb < 8; ++tb) uu8[tb] = __builtin_nontemporal_load((const v4u*)(proj + (R0 + 16 * tb + r) * DIN + 512 + colv + 8 * q));
.LBB0_511:
	v_lshl_add_u64 v[80:81], v[198:199], 0, s[20:21]
	v_add_co_u32_e32 v82, vcc, 0xf100000, v80
	s_mov_b32 s0, 0xf100000
	s_nop 0
	v_addc_co_u32_e32 v83, vcc, 0, v81, vcc
	global_load_dwordx4 v[118:121], v[82:83], off offset:2048 nt
	v_add_co_u32_e32 v82, vcc, 0xf10c000, v80
	s_waitcnt lgkmcnt(0)
	s_nop 0
	v_addc_co_u32_e32 v83, vcc, 0, v81, vcc
	global_load_dwordx4 v[112:115], v[82:83], off offset:2048 nt
	v_add_co_u32_e32 v82, vcc, 0xf118000, v80
	s_nop 0
	s_nop 0
	v_addc_co_u32_e32 v83, vcc, 0, v81, vcc
	global_load_dwordx4 v[108:111], v[82:83], off offset:2048 nt
	v_add_co_u32_e32 v82, vcc, 0xf124000, v80
	s_nop 0
	s_nop 0
	v_addc_co_u32_e32 v83, vcc, 0, v81, vcc
	global_load_dwordx4 v[104:107], v[82:83], off offset:2048 nt
	v_add_co_u32_e32 v82, vcc, 0xf130000, v80
	s_nop 0
	s_nop 0
	v_addc_co_u32_e32 v83, vcc, 0, v81, vcc
	global_load_dwordx4 v[100:103], v[82:83], off offset:2048 nt
	v_add_co_u32_e32 v82, vcc, 0xf13c000, v80
	s_nop 1
	v_addc_co_u32_e32 v83, vcc, 0, v81, vcc
	global_load_dwordx4 v[96:99], v[82:83], off offset:2048 nt
	v_add_co_u32_e32 v82, vcc, 0xf148000, v80
	s_nop 1
	v_addc_co_u32_e32 v83, vcc, 0, v81, vcc
	v_add_co_u32_e32 v80, vcc, 0xf154000, v80
	global_load_dwordx4 v[84:87], v[82:83], off offset:2048 nt
	s_nop 0
	v_addc_co_u32_e32 v81, vcc, 0, v81, vcc
	global_load_dwordx4 v[80:83], v[80:81], off offset:2048 nt
	s_nop 0
	global_load_dwordx4 v[88:91], v[178:179], off
	global_load_dwordx4 v[92:95], v[178:179], off offset:-16
	v_lshl_add_u64 v[248:249], v[188:189], 0, s[20:21]
	v_add_co_u32_e32 v250, vcc, s0, v248
	s_mov_b32 s0, 0xf10c000
	s_nop 0
	v_addc_co_u32_e32 v251, vcc, 0, v249, vcc
	global_load_dwordx4 v[140:143], v[250:251], off offset:1024 nt
	v_add_co_u32_e32 v250, vcc, s0, v248
	s_mov_b32 s0, 0xf118000
	s_nop 0
	v_addc_co_u32_e32 v251, vcc, 0, v249, vcc
	global_load_dwordx4 v[144:147], v[250:251], off offset:1024 nt
	v_add_co_u32_e32 v250, vcc, s0, v248
	s_mov_b32 s0, 0xf130000
	s_nop 0
	v_addc_co_u32_e32 v251, vcc, 0, v249, vcc
	global_load_dwordx4 v[148:151], v[250:251], off offset:1024 nt
	v_lshl_add_u64 v[250:251], v[190:191], 0, s[20:21]
	global_load_dwordx4 v[152:155], v[250:251], off nt
	v_add_co_u32_e32 v250, vcc, s0, v248
	s_mov_b32 s0, 0xf13c000
	s_nop 0
	v_addc_co_u32_e32 v251, vcc, 0, v249, vcc
	global_load_dwordx4 v[156:159], v[250:251], off offset:1024 nt
	v_add_co_u32_e32 v250, vcc, s0, v248
	s_mov_b32 s0, 0xf148000
	s_nop 0
	v_addc_co_u32_e32 v251, vcc, 0, v249, vcc
	global_load_dwordx4 v[238:241], v[250:251], off offset:1024 nt
	v_add_co_u32_e32 v248, vcc, s0, v248
	v_lshl_add_u64 v[160:161], v[186:187], 0, s[20:21]
	s_nop 0
	v_addc_co_u32_e32 v249, vcc, 0, v249, vcc
	global_load_dwordx4 v[248:251], v[248:249], off offset:1024 nt
	global_load_dwordx2 v[242:243], v[160:161], off offset:8 nt
	global_load_dwordx2 v[160:161], v[160:161], off nt
	s_waitcnt vmcnt(9)
	v_lshlrev_b32_e32 v117, 16, v119
	v_lshlrev_b32_e32 v116, 16, v118
	v_and_b32_e32 v119, 0xffff0000, v119
	v_and_b32_e32 v118, 0xffff0000, v118
	ds_read_b64 v[122:123], v218 offset:10240
	v_lshl_add_u64 v[178:179], v[178:179], 0, s[88:89]
	s_waitcnt lgkmcnt(0)
	v_pk_add_f32 v[116:117], v[116:117], v[122:123] op_sel_hi:[1,0] neg_lo:[0,1] neg_hi:[0,1]
	s_nop 0
	v_pk_mul_f32 v[124:125], v[122:123], v[116:117] op_sel:[1,0]
	v_pk_add_f32 v[118:119], v[118:119], v[122:123] op_sel_hi:[1,0] neg_lo:[0,1] neg_hi:[0,1]
	s_waitcnt vmcnt(9)
	v_mov_b32_e32 v116, v92
	v_mov_b32_e32 v117, v94
	v_pk_mul_f32 v[124:125], v[116:117], v[124:125]
	v_pk_mul_f32 v[118:119], v[122:123], v[118:119] op_sel:[1,0]
	v_mov_b32_e32 v94, v93
	v_pk_mul_f32 v[92:93], v[94:95], v[118:119]
	v_and_b32_sdwa v118, v125, v245 dst_sel:DWORD dst_unused:UNUSED_PAD src0_sel:WORD_1 src1_sel:DWORD
	v_and_b32_sdwa v119, v124, v245 dst_sel:DWORD dst_unused:UNUSED_PAD src0_sel:WORD_1 src1_sel:DWORD
	v_add3_u32 v124, v124, v119, s68
	v_add3_u32 v118, v125, v118, s68
	v_and_b32_sdwa v119, v93, v245 dst_sel:DWORD dst_unused:UNUSED_PAD src0_sel:WORD_1 src1_sel:DWORD
	v_and_b32_sdwa v125, v92, v245 dst_sel:DWORD dst_unused:UNUSED_PAD src0_sel:WORD_1 src1_sel:DWORD
	v_add3_u32 v93, v93, v119, s68
	v_add3_u32 v92, v92, v125, s68
	v_and_b32_e32 v93, 0xffff0000, v93
	v_and_b32_e32 v92, 0xffff0000, v92
	v_or_b32_sdwa v119, v93, v118 dst_sel:DWORD dst_unused:UNUSED_PAD src0_sel:DWORD src1_sel:WORD_1
	v_or_b32_sdwa v118, v92, v124 dst_sel:DWORD dst_unused:UNUSED_PAD src0_sel:DWORD src1_sel:WORD_1
	v_lshlrev_b32_e32 v93, 16, v121
	v_lshlrev_b32_e32 v92, 16, v120
	v_and_b32_e32 v121, 0xffff0000, v121
	v_and_b32_e32 v120, 0xffff0000, v120
	v_pk_add_f32 v[92:93], v[92:93], v[122:123] op_sel_hi:[1,0] neg_lo:[0,1] neg_hi:[0,1]
	v_pk_add_f32 v[120:121], v[120:121], v[122:123] op_sel_hi:[1,0] neg_lo:[0,1] neg_hi:[0,1]
	v_pk_mul_f32 v[124:125], v[122:123], v[92:93] op_sel:[1,0]
	v_mov_b32_e32 v93, v90
	v_pk_mul_f32 v[120:121], v[122:123], v[120:121] op_sel:[1,0]
	v_mov_b32_e32 v90, v89
	v_mov_b32_e32 v92, v88
	v_pk_mul_f32 v[88:89], v[90:91], v[120:121]
	v_pk_mul_f32 v[124:125], v[92:93], v[124:125]
	v_and_b32_sdwa v122, v89, v245 dst_sel:DWORD dst_unused:UNUSED_PAD src0_sel:WORD_1 src1_sel:DWORD
	v_and_b32_sdwa v123, v88, v245 dst_sel:DWORD dst_unused:UNUSED_PAD src0_sel:WORD_1 src1_sel:DWORD
	v_and_b32_sdwa v120, v125, v245 dst_sel:DWORD dst_unused:UNUSED_PAD src0_sel:WORD_1 src1_sel:DWORD
	v_and_b32_sdwa v121, v124, v245 dst_sel:DWORD dst_unused:UNUSED_PAD src0_sel:WORD_1 src1_sel:DWORD
	v_add3_u32 v89, v89, v122, s68
	v_add3_u32 v88, v88, v123, s68
	v_add3_u32 v121, v124, v121, s68
	v_add3_u32 v120, v125, v120, s68
	v_and_b32_e32 v89, 0xffff0000, v89
	v_and_b32_e32 v88, 0xffff0000, v88
	v_or_b32_sdwa v89, v89, v120 dst_sel:DWORD dst_unused:UNUSED_PAD src0_sel:DWORD src1_sel:WORD_1
	v_or_b32_sdwa v88, v88, v121 dst_sel:DWORD dst_unused:UNUSED_PAD src0_sel:DWORD src1_sel:WORD_1
	ds_write2_b64 v219, v[118:119], v[88:89] offset1:4
	ds_read_b64 v[88:89], v218 offset:10368
	v_lshlrev_b32_e32 v119, 16, v113
	v_lshlrev_b32_e32 v118, 16, v112
	v_and_b32_e32 v113, 0xffff0000, v113
	v_and_b32_e32 v112, 0xffff0000, v112
	s_waitcnt lgkmcnt(0)
; #define LAS __attribute__((address_space(3)))
; __device__ __forceinline__ unsigned pk2(float lo, float hi) { return f2bf(lo) | (f2bf(hi) << 16); }
; __device__ __forceinline__ float bflo(unsigned w) { return __uint_as_float(w << 16); }
; __device__ __forceinline__ float bfhi(unsigned w) { return __uint_as_float(w & 0xffff0000u); }
; __device__ __forceinline__ void sgu_item(LAS unsigned char* wl, const bf16* proj, bf16* ymix, const float* vstat, const float* sgu_g, const bf16* Wm, const float* sgu_b, int chunk, int h, int lane) {
;     ...
;         for (int i = 0; i < 8; ++i) { const int s = rsub + 16 * i; const f32x2 ms = st[s]; const v4u w = raw[i];
;             v2u lo, hi; lo.x = pk2((bflo(w.x) - ms.x) * ms.y * g0[0], (bfhi(w.x) - ms.x) * ms.y * g0[1]); lo.y = pk2((bflo(w.y) - ms.x) * ms.y * g0[2], (bfhi(w.y) - ms.x) * ms.y * g0[3]);
;             hi.x = pk2((bflo(w.z) - ms.x) * ms.y * g1[0], (bfhi(w.z) - ms.x) * ms.y * g1[1]); hi.y = pk2((bflo(w.w) - ms.x) * ms.y * g1[2], (bfhi(w.w) - ms.x) * ms.y * g1[3]);
;             *(LAS v2u*)(wl + s * VP2 + (4 * c16) * 2) = lo; *(LAS v2u*)(wl + s * VP2 + (16 + 4 * c16) * 2) = hi; }
	v_pk_add_f32 v[118:119], v[118:119], v[88:89] op_sel_hi:[1,0] neg_lo:[0,1] neg_hi:[0,1]
	v_pk_add_f32 v[112:113], v[112:113], v[88:89] op_sel_hi:[1,0] neg_lo:[0,1] neg_hi:[0,1]
	v_pk_mul_f32 v[118:119], v[88:89], v[118:119] op_sel:[1,0]
	v_pk_mul_f32 v[112:113], v[88:89], v[112:113] op_sel:[1,0]
	v_pk_mul_f32 v[118:119], v[116:117], v[118:119]
	v_pk_mul_f32 v[112:113], v[94:95], v[112:113]
	v_and_b32_sdwa v120, v119, v245 dst_sel:DWORD dst_unused:UNUSED_PAD src0_sel:WORD_1 src1_sel:DWORD
	v_and_b32_sdwa v121, v118, v245 dst_sel:DWORD dst_unused:UNUSED_PAD src0_sel:WORD_1 src1_sel:DWORD
	v_add3_u32 v118, v118, v121, s68
	v_add3_u32 v119, v119, v120, s68
	v_and_b32_sdwa v120, v113, v245 dst_sel:DWORD dst_unused:UNUSED_PAD src0_sel:WORD_1 src1_sel:DWORD
	v_and_b32_sdwa v121, v112, v245 dst_sel:DWORD dst_unused:UNUSED_PAD src0_sel:WORD_1 src1_sel:DWORD
	v_add3_u32 v113, v113, v120, s68
	v_add3_u32 v112, v112, v121, s68
	v_and_b32_e32 v113, 0xffff0000, v113
	v_and_b32_e32 v112, 0xffff0000, v112
	v_or_b32_sdwa v113, v113, v119 dst_sel:DWORD dst_unused:UNUSED_PAD src0_sel:DWORD src1_sel:WORD_1
	v_or_b32_sdwa v112, v112, v118 dst_sel:DWORD dst_unused:UNUSED_PAD src0_sel:DWORD src1_sel:WORD_1
	v_lshlrev_b32_e32 v119, 16, v115
	v_lshlrev_b32_e32 v118, 16, v114
	v_pk_add_f32 v[118:119], v[118:119], v[88:89] op_sel_hi:[1,0] neg_lo:[0,1] neg_hi:[0,1]
	v_and_b32_e32 v115, 0xffff0000, v115
	v_and_b32_e32 v114, 0xffff0000, v114
	v_pk_mul_f32 v[118:119], v[88:89], v[118:119] op_sel:[1,0]
	v_pk_add_f32 v[114:115], v[114:115], v[88:89] op_sel_hi:[1,0] neg_lo:[0,1] neg_hi:[0,1]
	v_pk_mul_f32 v[118:119], v[92:93], v[118:119]
	v_pk_mul_f32 v[88:89], v[88:89], v[114:115] op_sel:[1,0]
	v_and_b32_sdwa v114, v119, v245 dst_sel:DWORD dst_unused:UNUSED_PAD src0_sel:WORD_1 src1_sel:DWORD
	v_pk_mul_f32 v[88:89], v[90:91], v[88:89]
	v_and_b32_sdwa v115, v118, v245 dst_sel:DWORD dst_unused:UNUSED_PAD src0_sel:WORD_1 src1_sel:DWORD
	v_add3_u32 v115, v118, v115, s68
	v_add3_u32 v114, v119, v114, s68
	v_and_b32_sdwa v118, v89, v245 dst_sel:DWORD dst_unused:UNUSED_PAD src0_sel:WORD_1 src1_sel:DWORD
	v_and_b32_sdwa v119, v88, v245 dst_sel:DWORD dst_unused:UNUSED_PAD src0_sel:WORD_1 src1_sel:DWORD
	v_add3_u32 v89, v89, v118, s68
	v_add3_u32 v88, v88, v119, s68
	v_and_b32_e32 v89, 0xffff0000, v89
	v_and_b32_e32 v88, 0xffff0000, v88
	v_or_b32_sdwa v89, v89, v114 dst_sel:DWORD dst_unused:UNUSED_PAD src0_sel:DWORD src1_sel:WORD_1
	v_or_b32_sdwa v88, v88, v115 dst_sel:DWORD dst_unused:UNUSED_PAD src0_sel:DWORD src1_sel:WORD_1
	ds_write2_b64 v219, v[112:113], v[88:89] offset0:160 offset1:164
	ds_read_b64 v[112:113], v218 offset:10496
	v_lshlrev_b32_e32 v89, 16, v109
	v_lshlrev_b32_e32 v88, 16, v108
	v_and_b32_e32 v109, 0xffff0000, v109
	v_and_b32_e32 v108, 0xffff0000, v108
	s_waitcnt lgkmcnt(0)
	v_pk_add_f32 v[88:89], v[88:89], v[112:113] op_sel_hi:[1,0] neg_lo:[0,1] neg_hi:[0,1]
	v_pk_add_f32 v[108:109], v[108:109], v[112:113] op_sel_hi:[1,0] neg_lo:[0,1] neg_hi:[0,1]
	v_pk_mul_f32 v[88:89], v[112:113], v[88:89] op_sel:[1,0]
	v_pk_mul_f32 v[108:109], v[112:113], v[108:109] op_sel:[1,0]
	v_pk_mul_f32 v[88:89], v[116:117], v[88:89]
	v_pk_mul_f32 v[108:109], v[94:95], v[108:109]
	v_and_b32_sdwa v114, v89, v245 dst_sel:DWORD dst_unused:UNUSED_PAD src0_sel:WORD_1 src1_sel:DWORD
	v_and_b32_sdwa v115, v88, v245 dst_sel:DWORD dst_unused:UNUSED_PAD src0_sel:WORD_1 src1_sel:DWORD
	v_add3_u32 v88, v88, v115, s68
	v_add3_u32 v89, v89, v114, s68
	v_and_b32_sdwa v114, v109, v245 dst_sel:DWORD dst_unused:UNUSED_PAD src0_sel:WORD_1 src1_sel:DWORD
	v_and_b32_sdwa v115, v108, v245 dst_sel:DWORD dst_unused:UNUSED_PAD src0_sel:WORD_1 src1_sel:DWORD
	v_add3_u32 v109, v109, v114, s68
	v_add3_u32 v108, v108, v115, s68
	v_and_b32_e32 v109, 0xffff0000, v109
	v_and_b32_e32 v108, 0xffff0000, v108
	v_or_b32_sdwa v89, v109, v89 dst_sel:DWORD dst_unused:UNUSED_PAD src0_sel:DWORD src1_sel:WORD_1
	v_or_b32_sdwa v88, v108, v88 dst_sel:DWORD dst_unused:UNUSED_PAD src0_sel:DWORD src1_sel:WORD_1
	v_lshlrev_b32_e32 v109, 16, v111
	v_lshlrev_b32_e32 v108, 16, v110
	v_pk_add_f32 v[108:109], v[108:109], v[112:113] op_sel_hi:[1,0] neg_lo:[0,1] neg_hi:[0,1]
	v_and_b32_e32 v111, 0xffff0000, v111
	v_and_b32_e32 v110, 0xffff0000, v110
	v_pk_mul_f32 v[108:109], v[112:113], v[108:109] op_sel:[1,0]
	v_pk_add_f32 v[110:111], v[110:111], v[112:113] op_sel_hi:[1,0] neg_lo:[0,1] neg_hi:[0,1]
	v_pk_mul_f32 v[108:109], v[92:93], v[108:109]
	v_pk_mul_f32 v[110:111], v[112:113], v[110:111] op_sel:[1,0]
	v_and_b32_sdwa v112, v109, v245 dst_sel:DWORD dst_unused:UNUSED_PAD src0_sel:WORD_1 src1_sel:DWORD
	v_pk_mul_f32 v[110:111], v[90:91], v[110:111]
	v_and_b32_sdwa v113, v108, v245 dst_sel:DWORD dst_unused:UNUSED_PAD src0_sel:WORD_1 src1_sel:DWORD
	v_add3_u32 v108, v108, v113, s68
	v_add3_u32 v109, v109, v112, s68
	v_and_b32_sdwa v112, v111, v245 dst_sel:DWORD dst_unused:UNUSED_PAD src0_sel:WORD_1 src1_sel:DWORD
	v_and_b32_sdwa v113, v110, v245 dst_sel:DWORD dst_unused:UNUSED_PAD src0_sel:WORD_1 src1_sel:DWORD
	v_add3_u32 v111, v111, v112, s68
	v_add3_u32 v110, v110, v113, s68
	v_and_b32_e32 v111, 0xffff0000, v111
	v_and_b32_e32 v110, 0xffff0000, v110
	v_or_b32_sdwa v109, v111, v109 dst_sel:DWORD dst_unused:UNUSED_PAD src0_sel:DWORD src1_sel:WORD_1
	v_or_b32_sdwa v108, v110, v108 dst_sel:DWORD dst_unused:UNUSED_PAD src0_sel:DWORD src1_sel:WORD_1
	v_add_u32_e32 v110, 0x800, v219
	ds_write2_b64 v110, v[88:89], v[108:109] offset0:64 offset1:68
	ds_read_b64 v[88:89], v218 offset:10624
	v_lshlrev_b32_e32 v109, 16, v105
	v_lshlrev_b32_e32 v108, 16, v104
	v_and_b32_e32 v105, 0xffff0000, v105
	v_and_b32_e32 v104, 0xffff0000, v104
	s_waitcnt lgkmcnt(0)
; #define LAS __attribute__((address_space(3)))
; __device__ __forceinline__ unsigned pk2(float lo, float hi) { return f2bf(lo) | (f2bf(hi) << 16); }
; __device__ __forceinline__ float bflo(unsigned w) { return __uint_as_float(w << 16); }
; __device__ __forceinline__ float bfhi(unsigned w) { return __uint_as_float(w & 0xffff0000u); }
; __device__ __forceinline__ void sgu_item(LAS unsigned char* wl, const bf16* proj, bf16* ymix, const float* vstat, const float* sgu_g, const bf16* Wm, const float* sgu_b, int chunk, int h, int lane) {
;     ...
;         for (int i = 0; i < 8; ++i) { const int s = rsub + 16 * i; const f32x2 ms = st[s]; const v4u w = raw[i];
;             v2u lo, hi; lo.x = pk2((bflo(w.x) - ms.x) * ms.y * g0[0], (bfhi(w.x) - ms.x) * ms.y * g0[1]); lo.y = pk2((bflo(w.y) - ms.x) * ms.y * g0[2], (bfhi(w.y) - ms.x) * ms.y * g0[3]);
;             hi.x = pk2((bflo(w.z) - ms.x) * ms.y * g1[0], (bfhi(w.z) - ms.x) * ms.y * g1[1]); hi.y = pk2((bflo(w.w) - ms.x) * ms.y * g1[2], (bfhi(w.w) - ms.x) * ms.y * g1[3]);
;             *(LAS v2u*)(wl + s * VP2 + (4 * c16) * 2) = lo; *(LAS v2u*)(wl + s * VP2 + (16 + 4 * c16) * 2) = hi; }
	v_pk_add_f32 v[108:109], v[108:109], v[88:89] op_sel_hi:[1,0] neg_lo:[0,1] neg_hi:[0,1]
	v_pk_add_f32 v[104:105], v[104:105], v[88:89] op_sel_hi:[1,0] neg_lo:[0,1] neg_hi:[0,1]
	v_pk_mul_f32 v[108:109], v[88:89], v[108:109] op_sel:[1,0]
	v_pk_mul_f32 v[104:105], v[88:89], v[104:105] op_sel:[1,0]
	v_pk_mul_f32 v[108:109], v[116:117], v[108:109]
	v_pk_mul_f32 v[104:105], v[94:95], v[104:105]
	v_and_b32_sdwa v111, v109, v245 dst_sel:DWORD dst_unused:UNUSED_PAD src0_sel:WORD_1 src1_sel:DWORD
	v_and_b32_sdwa v112, v108, v245 dst_sel:DWORD dst_unused:UNUSED_PAD src0_sel:WORD_1 src1_sel:DWORD
	v_add3_u32 v108, v108, v112, s68
	v_add3_u32 v109, v109, v111, s68
	v_and_b32_sdwa v111, v105, v245 dst_sel:DWORD dst_unused:UNUSED_PAD src0_sel:WORD_1 src1_sel:DWORD
	v_and_b32_sdwa v112, v104, v245 dst_sel:DWORD dst_unused:UNUSED_PAD src0_sel:WORD_1 src1_sel:DWORD
	v_add3_u32 v105, v105, v111, s68
	v_add3_u32 v104, v104, v112, s68
	v_and_b32_e32 v105, 0xffff0000, v105
	v_and_b32_e32 v104, 0xffff0000, v104
	v_or_b32_sdwa v105, v105, v109 dst_sel:DWORD dst_unused:UNUSED_PAD src0_sel:DWORD src1_sel:WORD_1
	v_or_b32_sdwa v104, v104, v108 dst_sel:DWORD dst_unused:UNUSED_PAD src0_sel:DWORD src1_sel:WORD_1
	v_lshlrev_b32_e32 v109, 16, v107
	v_lshlrev_b32_e32 v108, 16, v106
	v_pk_add_f32 v[108:109], v[108:109], v[88:89] op_sel_hi:[1,0] neg_lo:[0,1] neg_hi:[0,1]
	v_and_b32_e32 v107, 0xffff0000, v107
	v_and_b32_e32 v106, 0xffff0000, v106
	v_pk_mul_f32 v[108:109], v[88:89], v[108:109] op_sel:[1,0]
	v_pk_add_f32 v[106:107], v[106:107], v[88:89] op_sel_hi:[1,0] neg_lo:[0,1] neg_hi:[0,1]
	v_pk_mul_f32 v[108:109], v[92:93], v[108:109]
	v_pk_mul_f32 v[88:89], v[88:89], v[106:107] op_sel:[1,0]
	v_and_b32_sdwa v106, v109, v245 dst_sel:DWORD dst_unused:UNUSED_PAD src0_sel:WORD_1 src1_sel:DWORD
	v_pk_mul_f32 v[88:89], v[90:91], v[88:89]
	v_and_b32_sdwa v107, v108, v245 dst_sel:DWORD dst_unused:UNUSED_PAD src0_sel:WORD_1 src1_sel:DWORD
	v_add3_u32 v107, v108, v107, s68
	v_add3_u32 v106, v109, v106, s68
	v_and_b32_sdwa v108, v89, v245 dst_sel:DWORD dst_unused:UNUSED_PAD src0_sel:WORD_1 src1_sel:DWORD
	v_and_b32_sdwa v109, v88, v245 dst_sel:DWORD dst_unused:UNUSED_PAD src0_sel:WORD_1 src1_sel:DWORD
	v_add3_u32 v89, v89, v108, s68
	v_add3_u32 v88, v88, v109, s68
	v_and_b32_e32 v89, 0xffff0000, v89
	v_and_b32_e32 v88, 0xffff0000, v88
	v_or_b32_sdwa v89, v89, v106 dst_sel:DWORD dst_unused:UNUSED_PAD src0_sel:DWORD src1_sel:WORD_1
	v_or_b32_sdwa v88, v88, v107 dst_sel:DWORD dst_unused:UNUSED_PAD src0_sel:DWORD src1_sel:WORD_1
	ds_write2_b64 v110, v[104:105], v[88:89] offset0:224 offset1:228
	ds_read_b64 v[104:105], v218 offset:10752
	v_lshlrev_b32_e32 v89, 16, v101
	v_lshlrev_b32_e32 v88, 16, v100
	v_and_b32_e32 v101, 0xffff0000, v101
	v_and_b32_e32 v100, 0xffff0000, v100
	s_waitcnt lgkmcnt(0)
	v_pk_add_f32 v[88:89], v[88:89], v[104:105] op_sel_hi:[1,0] neg_lo:[0,1] neg_hi:[0,1]
	v_pk_add_f32 v[100:101], v[100:101], v[104:105] op_sel_hi:[1,0] neg_lo:[0,1] neg_hi:[0,1]
	v_pk_mul_f32 v[88:89], v[104:105], v[88:89] op_sel:[1,0]
	v_pk_mul_f32 v[100:101], v[104:105], v[100:101] op_sel:[1,0]
	v_pk_mul_f32 v[88:89], v[116:117], v[88:89]
	v_pk_mul_f32 v[100:101], v[94:95], v[100:101]
	v_and_b32_sdwa v106, v89, v245 dst_sel:DWORD dst_unused:UNUSED_PAD src0_sel:WORD_1 src1_sel:DWORD
	v_and_b32_sdwa v107, v88, v245 dst_sel:DWORD dst_unused:UNUSED_PAD src0_sel:WORD_1 src1_sel:DWORD
	v_add3_u32 v88, v88, v107, s68
	v_add3_u32 v89, v89, v106, s68
	v_and_b32_sdwa v106, v101, v245 dst_sel:DWORD dst_unused:UNUSED_PAD src0_sel:WORD_1 src1_sel:DWORD
	v_and_b32_sdwa v107, v100, v245 dst_sel:DWORD dst_unused:UNUSED_PAD src0_sel:WORD_1 src1_sel:DWORD
	v_add3_u32 v101, v101, v106, s68
	v_add3_u32 v100, v100, v107, s68
	v_and_b32_e32 v101, 0xffff0000, v101
	v_and_b32_e32 v100, 0xffff0000, v100
	v_or_b32_sdwa v89, v101, v89 dst_sel:DWORD dst_unused:UNUSED_PAD src0_sel:DWORD src1_sel:WORD_1
	v_or_b32_sdwa v88, v100, v88 dst_sel:DWORD dst_unused:UNUSED_PAD src0_sel:DWORD src1_sel:WORD_1
	v_lshlrev_b32_e32 v101, 16, v103
	v_lshlrev_b32_e32 v100, 16, v102
	v_pk_add_f32 v[100:101], v[100:101], v[104:105] op_sel_hi:[1,0] neg_lo:[0,1] neg_hi:[0,1]
	v_and_b32_e32 v103, 0xffff0000, v103
	v_and_b32_e32 v102, 0xffff0000, v102
	v_pk_mul_f32 v[100:101], v[104:105], v[100:101] op_sel:[1,0]
	v_pk_add_f32 v[102:103], v[102:103], v[104:105] op_sel_hi:[1,0] neg_lo:[0,1] neg_hi:[0,1]
	v_pk_mul_f32 v[100:101], v[92:93], v[100:101]
	v_pk_mul_f32 v[102:103], v[104:105], v[102:103] op_sel:[1,0]
	v_and_b32_sdwa v104, v101, v245 dst_sel:DWORD dst_unused:UNUSED_PAD src0_sel:WORD_1 src1_sel:DWORD
	v_pk_mul_f32 v[102:103], v[90:91], v[102:103]
	v_and_b32_sdwa v105, v100, v245 dst_sel:DWORD dst_unused:UNUSED_PAD src0_sel:WORD_1 src1_sel:DWORD
	v_add3_u32 v100, v100, v105, s68
	v_add3_u32 v101, v101, v104, s68
	v_and_b32_sdwa v104, v103, v245 dst_sel:DWORD dst_unused:UNUSED_PAD src0_sel:WORD_1 src1_sel:DWORD
	v_and_b32_sdwa v105, v102, v245 dst_sel:DWORD dst_unused:UNUSED_PAD src0_sel:WORD_1 src1_sel:DWORD
	v_add3_u32 v103, v103, v104, s68
	v_add3_u32 v102, v102, v105, s68
	v_and_b32_e32 v103, 0xffff0000, v103
	v_and_b32_e32 v102, 0xffff0000, v102
	v_or_b32_sdwa v101, v103, v101 dst_sel:DWORD dst_unused:UNUSED_PAD src0_sel:DWORD src1_sel:WORD_1
	v_or_b32_sdwa v100, v102, v100 dst_sel:DWORD dst_unused:UNUSED_PAD src0_sel:DWORD src1_sel:WORD_1
	v_add_u32_e32 v102, 0x1000, v219
	ds_write2_b64 v102, v[88:89], v[100:101] offset0:128 offset1:132
	ds_read_b64 v[88:89], v218 offset:10880
	v_lshlrev_b32_e32 v101, 16, v97
	v_lshlrev_b32_e32 v100, 16, v96
	v_and_b32_e32 v97, 0xffff0000, v97
	v_and_b32_e32 v96, 0xffff0000, v96
	s_waitcnt lgkmcnt(0)
; #define LAS __attribute__((address_space(3)))
; __device__ __forceinline__ unsigned pk2(float lo, float hi) { return f2bf(lo) | (f2bf(hi) << 16); }
; __device__ __forceinline__ float bflo(unsigned w) { return __uint_as_float(w << 16); }
; __device__ __forceinline__ float bfhi(unsigned w) { return __uint_as_float(w & 0xffff0000u); }
; __device__ __forceinline__ void sgu_item(LAS unsigned char* wl, const bf16* proj, bf16* ymix, const float* vstat, const float* sgu_g, const bf16* Wm, const float* sgu_b, int chunk, int h, int lane) {
;     ...
;         for (int i = 0; i < 8; ++i) { const int s = rsub + 16 * i; const f32x2 ms = st[s]; const v4u w = raw[i];
;             v2u lo, hi; lo.x = pk2((bflo(w.x) - ms.x) * ms.y * g0[0], (bfhi(w.x) - ms.x) * ms.y * g0[1]); lo.y = pk2((bflo(w.y) - ms.x) * ms.y * g0[2], (bfhi(w.y) - ms.x) * ms.y * g0[3]);
;             hi.x = pk2((bflo(w.z) - ms.x) * ms.y * g1[0], (bfhi(w.z) - ms.x) * ms.y * g1[1]); hi.y = pk2((bflo(w.w) - ms.x) * ms.y * g1[2], (bfhi(w.w) - ms.x) * ms.y * g1[3]);
;             *(LAS v2u*)(wl + s * VP2 + (4 * c16) * 2) = lo; *(LAS v2u*)(wl + s * VP2 + (16 + 4 * c16) * 2) = hi; }
	v_pk_add_f32 v[100:101], v[100:101], v[88:89] op_sel_hi:[1,0] neg_lo:[0,1] neg_hi:[0,1]
	v_pk_add_f32 v[96:97], v[96:97], v[88:89] op_sel_hi:[1,0] neg_lo:[0,1] neg_hi:[0,1]
	v_pk_mul_f32 v[100:101], v[88:89], v[100:101] op_sel:[1,0]
	v_pk_mul_f32 v[96:97], v[88:89], v[96:97] op_sel:[1,0]
	v_pk_mul_f32 v[100:101], v[116:117], v[100:101]
	v_pk_mul_f32 v[96:97], v[94:95], v[96:97]
	v_and_b32_sdwa v102, v101, v245 dst_sel:DWORD dst_unused:UNUSED_PAD src0_sel:WORD_1 src1_sel:DWORD
	v_and_b32_sdwa v103, v100, v245 dst_sel:DWORD dst_unused:UNUSED_PAD src0_sel:WORD_1 src1_sel:DWORD
	v_add3_u32 v100, v100, v103, s68
	v_add3_u32 v101, v101, v102, s68
	v_and_b32_sdwa v102, v97, v245 dst_sel:DWORD dst_unused:UNUSED_PAD src0_sel:WORD_1 src1_sel:DWORD
	v_and_b32_sdwa v103, v96, v245 dst_sel:DWORD dst_unused:UNUSED_PAD src0_sel:WORD_1 src1_sel:DWORD
	v_add3_u32 v97, v97, v102, s68
	v_add3_u32 v96, v96, v103, s68
	v_and_b32_e32 v97, 0xffff0000, v97
	v_and_b32_e32 v96, 0xffff0000, v96
	v_or_b32_sdwa v97, v97, v101 dst_sel:DWORD dst_unused:UNUSED_PAD src0_sel:DWORD src1_sel:WORD_1
	v_or_b32_sdwa v96, v96, v100 dst_sel:DWORD dst_unused:UNUSED_PAD src0_sel:DWORD src1_sel:WORD_1
	v_lshlrev_b32_e32 v101, 16, v99
	v_lshlrev_b32_e32 v100, 16, v98
	v_pk_add_f32 v[100:101], v[100:101], v[88:89] op_sel_hi:[1,0] neg_lo:[0,1] neg_hi:[0,1]
	v_and_b32_e32 v99, 0xffff0000, v99
	v_and_b32_e32 v98, 0xffff0000, v98
	v_pk_mul_f32 v[100:101], v[88:89], v[100:101] op_sel:[1,0]
	v_pk_add_f32 v[98:99], v[98:99], v[88:89] op_sel_hi:[1,0] neg_lo:[0,1] neg_hi:[0,1]
	v_pk_mul_f32 v[100:101], v[92:93], v[100:101]
	v_pk_mul_f32 v[88:89], v[88:89], v[98:99] op_sel:[1,0]
	v_and_b32_sdwa v98, v101, v245 dst_sel:DWORD dst_unused:UNUSED_PAD src0_sel:WORD_1 src1_sel:DWORD
	v_pk_mul_f32 v[88:89], v[90:91], v[88:89]
	v_and_b32_sdwa v99, v100, v245 dst_sel:DWORD dst_unused:UNUSED_PAD src0_sel:WORD_1 src1_sel:DWORD
	v_add3_u32 v99, v100, v99, s68
	v_add3_u32 v98, v101, v98, s68
	v_and_b32_sdwa v100, v89, v245 dst_sel:DWORD dst_unused:UNUSED_PAD src0_sel:WORD_1 src1_sel:DWORD
	v_and_b32_sdwa v101, v88, v245 dst_sel:DWORD dst_unused:UNUSED_PAD src0_sel:WORD_1 src1_sel:DWORD
	v_add3_u32 v89, v89, v100, s68
	v_add3_u32 v88, v88, v101, s68
	v_and_b32_e32 v89, 0xffff0000, v89
	v_and_b32_e32 v88, 0xffff0000, v88
	v_or_b32_sdwa v89, v89, v98 dst_sel:DWORD dst_unused:UNUSED_PAD src0_sel:DWORD src1_sel:WORD_1
	v_or_b32_sdwa v88, v88, v99 dst_sel:DWORD dst_unused:UNUSED_PAD src0_sel:DWORD src1_sel:WORD_1
	v_add_u32_e32 v98, 0x1800, v219
	ds_write2_b64 v98, v[96:97], v[88:89] offset0:32 offset1:36
	ds_read_b64 v[88:89], v218 offset:11008
	v_lshlrev_b32_e32 v97, 16, v85
	v_lshlrev_b32_e32 v96, 16, v84
	v_and_b32_e32 v85, 0xffff0000, v85
	v_and_b32_e32 v84, 0xffff0000, v84
	s_waitcnt lgkmcnt(0)
	v_pk_add_f32 v[96:97], v[96:97], v[88:89] op_sel_hi:[1,0] neg_lo:[0,1] neg_hi:[0,1]
	v_pk_add_f32 v[84:85], v[84:85], v[88:89] op_sel_hi:[1,0] neg_lo:[0,1] neg_hi:[0,1]
	v_pk_mul_f32 v[96:97], v[88:89], v[96:97] op_sel:[1,0]
	v_pk_mul_f32 v[84:85], v[88:89], v[84:85] op_sel:[1,0]
	v_pk_mul_f32 v[96:97], v[116:117], v[96:97]
	v_pk_mul_f32 v[84:85], v[94:95], v[84:85]
	v_and_b32_sdwa v99, v97, v245 dst_sel:DWORD dst_unused:UNUSED_PAD src0_sel:WORD_1 src1_sel:DWORD
	v_and_b32_sdwa v100, v96, v245 dst_sel:DWORD dst_unused:UNUSED_PAD src0_sel:WORD_1 src1_sel:DWORD
	v_add3_u32 v96, v96, v100, s68
	v_add3_u32 v97, v97, v99, s68
	v_and_b32_sdwa v99, v85, v245 dst_sel:DWORD dst_unused:UNUSED_PAD src0_sel:WORD_1 src1_sel:DWORD
	v_and_b32_sdwa v100, v84, v245 dst_sel:DWORD dst_unused:UNUSED_PAD src0_sel:WORD_1 src1_sel:DWORD
	v_add3_u32 v85, v85, v99, s68
	v_add3_u32 v84, v84, v100, s68
	v_and_b32_e32 v85, 0xffff0000, v85
	v_and_b32_e32 v84, 0xffff0000, v84
	v_or_b32_sdwa v85, v85, v97 dst_sel:DWORD dst_unused:UNUSED_PAD src0_sel:DWORD src1_sel:WORD_1
	v_or_b32_sdwa v84, v84, v96 dst_sel:DWORD dst_unused:UNUSED_PAD src0_sel:DWORD src1_sel:WORD_1
	v_lshlrev_b32_e32 v97, 16, v87
	v_lshlrev_b32_e32 v96, 16, v86
	v_pk_add_f32 v[96:97], v[96:97], v[88:89] op_sel_hi:[1,0] neg_lo:[0,1] neg_hi:[0,1]
	v_and_b32_e32 v87, 0xffff0000, v87
	v_and_b32_e32 v86, 0xffff0000, v86
	v_pk_mul_f32 v[96:97], v[88:89], v[96:97] op_sel:[1,0]
	v_pk_add_f32 v[86:87], v[86:87], v[88:89] op_sel_hi:[1,0] neg_lo:[0,1] neg_hi:[0,1]
	v_pk_mul_f32 v[96:97], v[92:93], v[96:97]
	v_pk_mul_f32 v[86:87], v[88:89], v[86:87] op_sel:[1,0]
	v_and_b32_sdwa v88, v97, v245 dst_sel:DWORD dst_unused:UNUSED_PAD src0_sel:WORD_1 src1_sel:DWORD
	v_pk_mul_f32 v[86:87], v[90:91], v[86:87]
	v_and_b32_sdwa v89, v96, v245 dst_sel:DWORD dst_unused:UNUSED_PAD src0_sel:WORD_1 src1_sel:DWORD
	v_add3_u32 v89, v96, v89, s68
	v_add3_u32 v88, v97, v88, s68
	v_and_b32_sdwa v96, v87, v245 dst_sel:DWORD dst_unused:UNUSED_PAD src0_sel:WORD_1 src1_sel:DWORD
	v_and_b32_sdwa v97, v86, v245 dst_sel:DWORD dst_unused:UNUSED_PAD src0_sel:WORD_1 src1_sel:DWORD
	v_add3_u32 v87, v87, v96, s68
	v_add3_u32 v86, v86, v97, s68
	v_and_b32_e32 v87, 0xffff0000, v87
	v_and_b32_e32 v86, 0xffff0000, v86
	v_or_b32_sdwa v87, v87, v88 dst_sel:DWORD dst_unused:UNUSED_PAD src0_sel:DWORD src1_sel:WORD_1
	v_or_b32_sdwa v86, v86, v89 dst_sel:DWORD dst_unused:UNUSED_PAD src0_sel:DWORD src1_sel:WORD_1
	ds_write2_b64 v98, v[84:85], v[86:87] offset0:192 offset1:196
	ds_read_b64 v[84:85], v218 offset:11136
	v_lshlrev_b32_e32 v87, 16, v81
	v_lshlrev_b32_e32 v86, 16, v80
	v_and_b32_e32 v81, 0xffff0000, v81
	v_and_b32_e32 v80, 0xffff0000, v80
	s_waitcnt lgkmcnt(0)
; #define LAS __attribute__((address_space(3)))
; #define MFMA16(a, b, c) __builtin_amdgcn_mfma_f32_16x16x32_bf16((a), (b), (c), 0, 0, 0)
; __device__ __forceinline__ unsigned pk2(float lo, float hi) { return f2bf(lo) | (f2bf(hi) << 16); }
; __device__ __forceinline__ float bflo(unsigned w) { return __uint_as_float(w << 16); }
; __device__ __forceinline__ float bfhi(unsigned w) { return __uint_as_float(w & 0xffff0000u); }
; #define LDS_WAIT() asm volatile("s_waitcnt lgkmcnt(0)" ::: "memory")
; __device__ __forceinline__ void sgu_item(LAS unsigned char* wl, const bf16* proj, bf16* ymix, const float* vstat, const float* sgu_g, const bf16* Wm, const float* sgu_b, int chunk, int h, int lane) {
;     ...
;         for (int i = 0; i < 8; ++i) { const int s = rsub + 16 * i; const f32x2 ms = st[s]; const v4u w = raw[i];
;             v2u lo, hi; lo.x = pk2((bflo(w.x) - ms.x) * ms.y * g0[0], (bfhi(w.x) - ms.x) * ms.y * g0[1]); lo.y = pk2((bflo(w.y) - ms.x) * ms.y * g0[2], (bfhi(w.y) - ms.x) * ms.y * g0[3]);
;             hi.x = pk2((bflo(w.z) - ms.x) * ms.y * g1[0], (bfhi(w.z) - ms.x) * ms.y * g1[1]); hi.y = pk2((bflo(w.w) - ms.x) * ms.y * g1[2], (bfhi(w.w) - ms.x) * ms.y * g1[3]);
;             *(LAS v2u*)(wl + s * VP2 + (4 * c16) * 2) = lo; *(LAS v2u*)(wl + s * VP2 + (16 + 4 * c16) * 2) = hi; }
;         v4u uu8[8];
; #pragma unroll
;         for (int tb = 0; tb < 8; ++tb) uu8[tb] = __builtin_nontemporal_load((const v4u*)(proj + (R0 + 16 * tb + r) * DIN + 512 + colv + 8 * q));
;         LDS_WAIT();
;         v2u olo[8];
; #pragma unroll
;         for (int n = 0; n < 2; ++n) {
;             f32x4 z[8];
; #pragma unroll
;             for (int tb = 0; tb < 8; ++tb) z[tb] = (f32x4){0.f, 0.f, 0.f, 0.f};
;             int f = 0;
; #pragma unroll
;             for (int ks = 0; ks < 4; ++ks) {
;                 LAS unsigned char* ad = wl + (ks * 32 + 8 * q + (r >> 2)) * VP2 + (16 * n) * 2 + 8 * (r & 3);
;                 const s16x4 lo = __builtin_bit_cast(s16x4, __builtin_amdgcn_ds_read_tr16_b64_v4i16((LAS s16x4*)ad));
;                 const s16x4 hi = __builtin_bit_cast(s16x4, __builtin_amdgcn_ds_read_tr16_b64_v4i16((LAS s16x4*)(ad + 4 * VP2)));
;                 const bf16x8 vf = __builtin_shufflevector(lo, hi, 0, 1, 2, 3, 4, 5, 6, 7);
; #pragma unroll
;                 for (int tb = 2 * ks; tb < 8; ++tb) z[tb] = MFMA16(vf, wmf[f++], z[tb]);
	v_pk_add_f32 v[86:87], v[86:87], v[84:85] op_sel_hi:[1,0] neg_lo:[0,1] neg_hi:[0,1]
	v_pk_add_f32 v[80:81], v[80:81], v[84:85] op_sel_hi:[1,0] neg_lo:[0,1] neg_hi:[0,1]
	v_pk_mul_f32 v[86:87], v[84:85], v[86:87] op_sel:[1,0]
	v_pk_mul_f32 v[80:81], v[84:85], v[80:81] op_sel:[1,0]
	v_pk_mul_f32 v[86:87], v[116:117], v[86:87]
	v_pk_mul_f32 v[80:81], v[94:95], v[80:81]
	v_and_b32_sdwa v88, v87, v245 dst_sel:DWORD dst_unused:UNUSED_PAD src0_sel:WORD_1 src1_sel:DWORD
	v_and_b32_sdwa v89, v86, v245 dst_sel:DWORD dst_unused:UNUSED_PAD src0_sel:WORD_1 src1_sel:DWORD
	v_add3_u32 v86, v86, v89, s68
	v_add3_u32 v87, v87, v88, s68
	v_and_b32_sdwa v88, v81, v245 dst_sel:DWORD dst_unused:UNUSED_PAD src0_sel:WORD_1 src1_sel:DWORD
	v_and_b32_sdwa v89, v80, v245 dst_sel:DWORD dst_unused:UNUSED_PAD src0_sel:WORD_1 src1_sel:DWORD
	v_add3_u32 v81, v81, v88, s68
	v_add3_u32 v80, v80, v89, s68
	v_and_b32_e32 v81, 0xffff0000, v81
	v_and_b32_e32 v80, 0xffff0000, v80
	v_or_b32_sdwa v81, v81, v87 dst_sel:DWORD dst_unused:UNUSED_PAD src0_sel:DWORD src1_sel:WORD_1
	v_or_b32_sdwa v80, v80, v86 dst_sel:DWORD dst_unused:UNUSED_PAD src0_sel:DWORD src1_sel:WORD_1
	v_lshlrev_b32_e32 v87, 16, v83
	v_lshlrev_b32_e32 v86, 16, v82
	v_pk_add_f32 v[86:87], v[86:87], v[84:85] op_sel_hi:[1,0] neg_lo:[0,1] neg_hi:[0,1]
	v_and_b32_e32 v83, 0xffff0000, v83
	v_and_b32_e32 v82, 0xffff0000, v82
	v_pk_mul_f32 v[86:87], v[84:85], v[86:87] op_sel:[1,0]
	v_pk_add_f32 v[82:83], v[82:83], v[84:85] op_sel_hi:[1,0] neg_lo:[0,1] neg_hi:[0,1]
	v_pk_mul_f32 v[86:87], v[92:93], v[86:87]
	v_pk_mul_f32 v[82:83], v[84:85], v[82:83] op_sel:[1,0]
	v_and_b32_sdwa v84, v87, v245 dst_sel:DWORD dst_unused:UNUSED_PAD src0_sel:WORD_1 src1_sel:DWORD
	v_pk_mul_f32 v[82:83], v[90:91], v[82:83]
	v_and_b32_sdwa v85, v86, v245 dst_sel:DWORD dst_unused:UNUSED_PAD src0_sel:WORD_1 src1_sel:DWORD
	v_add3_u32 v85, v86, v85, s68
	v_add3_u32 v84, v87, v84, s68
	v_and_b32_sdwa v86, v83, v245 dst_sel:DWORD dst_unused:UNUSED_PAD src0_sel:WORD_1 src1_sel:DWORD
	v_and_b32_sdwa v87, v82, v245 dst_sel:DWORD dst_unused:UNUSED_PAD src0_sel:WORD_1 src1_sel:DWORD
	v_add3_u32 v83, v83, v86, s68
	v_add3_u32 v82, v82, v87, s68
	v_and_b32_e32 v83, 0xffff0000, v83
	v_and_b32_e32 v82, 0xffff0000, v82
	v_or_b32_sdwa v83, v83, v84 dst_sel:DWORD dst_unused:UNUSED_PAD src0_sel:DWORD src1_sel:WORD_1
	v_or_b32_sdwa v82, v82, v85 dst_sel:DWORD dst_unused:UNUSED_PAD src0_sel:DWORD src1_sel:WORD_1
	v_add_u32_e32 v84, 0x2000, v219
	ds_write2_b64 v84, v[80:81], v[82:83] offset0:96 offset1:100
	s_mov_b32 s0, 0x10900000
	s_waitcnt lgkmcnt(0)
	ds_read_b64_tr_b16 v[116:117], v220 offset:320
	ds_read_b64_tr_b16 v[114:115], v220
	ds_read_b64_tr_b16 v[112:113], v220 offset:32
	ds_read_b64_tr_b16 v[208:209], v220 offset:2560
	ds_read_b64_tr_b16 v[210:211], v220 offset:2880
	s_waitcnt lgkmcnt(0)
	v_mfma_f32_16x16x32_bf16 v[118:121], v[114:117], v[0:3], 0
	v_mfma_f32_16x16x32_bf16 v[122:125], v[114:117], v[4:7], 0
	s_nop 6
	v_mov_b32_e32 v138, v119
	v_mov_b32_e32 v119, v120
	v_pk_add_f32 v[118:119], v[162:163], v[118:119]
	v_mfma_f32_16x16x32_bf16 v[126:129], v[114:117], v[8:11], 0
	v_mov_b32_e32 v139, v121
	v_pk_add_f32 v[138:139], v[162:163], v[138:139]
	v_mfma_f32_16x16x32_bf16 v[130:133], v[114:117], v[16:19], 0
	v_mfma_f32_16x16x32_bf16 v[134:137], v[114:117], v[24:27], 0
	v_mfma_f32_16x16x32_bf16 v[200:203], v[114:117], v[48:51], 0
	v_mfma_f32_16x16x32_bf16 v[204:207], v[114:117], v[32:35], 0
	v_mfma_f32_16x16x32_bf16 v[114:117], v[114:117], v[40:43], 0
	v_mfma_f32_16x16x32_bf16 v[126:129], v[208:211], v[12:15], v[126:129]
	v_mfma_f32_16x16x32_bf16 v[130:133], v[208:211], v[20:23], v[130:133]
	v_mfma_f32_16x16x32_bf16 v[134:137], v[208:211], v[28:31], v[134:137]
	v_mfma_f32_16x16x32_bf16 v[200:203], v[208:211], v[56:59], v[200:203]
	v_mfma_f32_16x16x32_bf16 v[204:207], v[208:211], v[36:39], v[204:207]
	v_mfma_f32_16x16x32_bf16 v[114:117], v[208:211], v[44:47], v[114:117]
	ds_read_b64_tr_b16 v[208:209], v220 offset:5120
	ds_read_b64_tr_b16 v[210:211], v220 offset:5440
	s_waitcnt lgkmcnt(0)
	v_mfma_f32_16x16x32_bf16 v[222:225], v[208:211], v[60:63], v[200:203]
	v_mfma_f32_16x16x32_bf16 v[200:203], v[208:211], v[64:67], v[204:207]
	s_nop 2
	ds_read_b64_tr_b16 v[204:205], v220 offset:7680
	ds_read_b64_tr_b16 v[206:207], v220 offset:8000
	s_waitcnt lgkmcnt(0)
	v_mfma_f32_16x16x32_bf16 v[226:229], v[204:207], v[68:71], v[200:203]
	s_waitcnt vmcnt(0)
; #define LAS __attribute__((address_space(3)))
; #define MFMA16(a, b, c) __builtin_amdgcn_mfma_f32_16x16x32_bf16((a), (b), (c), 0, 0, 0)
; __device__ __forceinline__ unsigned pk2(float lo, float hi) { return f2bf(lo) | (f2bf(hi) << 16); }
; __device__ __forceinline__ float bflo(unsigned w) { return __uint_as_float(w << 16); }
; __device__ __forceinline__ float bfhi(unsigned w) { return __uint_as_float(w & 0xffff0000u); }
; __device__ __forceinline__ void sgu_item(LAS unsigned char* wl, const bf16* proj, bf16* ymix, const float* vstat, const float* sgu_g, const bf16* Wm, const float* sgu_b, int chunk, int h, int lane) {
;     ...
;         for (int n = 0; n < 2; ++n) {
;             f32x4 z[8];
; #pragma unroll
;             for (int tb = 0; tb < 8; ++tb) z[tb] = (f32x4){0.f, 0.f, 0.f, 0.f};
;             int f = 0;
; #pragma unroll
;             for (int ks = 0; ks < 4; ++ks) {
;                 LAS unsigned char* ad = wl + (ks * 32 + 8 * q + (r >> 2)) * VP2 + (16 * n) * 2 + 8 * (r & 3);
;                 const s16x4 lo = __builtin_bit_cast(s16x4, __builtin_amdgcn_ds_read_tr16_b64_v4i16((LAS s16x4*)ad));
;                 const s16x4 hi = __builtin_bit_cast(s16x4, __builtin_amdgcn_ds_read_tr16_b64_v4i16((LAS s16x4*)(ad + 4 * VP2)));
;                 const bf16x8 vf = __builtin_shufflevector(lo, hi, 0, 1, 2, 3, 4, 5, 6, 7);
; #pragma unroll
;                 for (int tb = 2 * ks; tb < 8; ++tb) z[tb] = MFMA16(vf, wmf[f++], z[tb]);
;             }
; #pragma unroll
;             for (int tb = 0; tb < 8; ++tb) { const v4u uu = uu8[tb]; const unsigned ux = n == 0 ? uu.x : uu.z, uy = n == 0 ? uu.y : uu.w;
;                 v2u o; o.x = pk2(bflo(ux) * (z[tb][0] + bias[tb]), bfhi(ux) * (z[tb][1] + bias[tb])); o.y = pk2(bflo(uy) * (z[tb][2] + bias[tb]), bfhi(uy) * (z[tb][3] + bias[tb]));
	s_nop 1
	v_and_b32_e32 v201, 0xffff0000, v141
	v_and_b32_e32 v200, 0xffff0000, v140
	v_lshlrev_b32_e32 v105, 16, v141
	v_lshlrev_b32_e32 v104, 16, v140
	v_pk_mul_f32 v[214:215], v[118:119], v[104:105]
	v_mov_b32_e32 v104, v123
	v_mov_b32_e32 v105, v125
	v_pk_add_f32 v[104:105], v[164:165], v[104:105]
	v_and_b32_e32 v119, 0xffff0000, v145
	v_and_b32_e32 v118, 0xffff0000, v144
	v_mov_b32_e32 v123, v124
	v_mfma_f32_16x16x32_bf16 v[114:117], v[208:211], v[72:75], v[114:117]
	v_mul_f32_e64 v212, v104, v118
	v_mul_f32_e64 v213, v105, v119
	v_pk_add_f32 v[104:105], v[164:165], v[122:123]
	v_lshlrev_b32_e32 v101, 16, v145
	v_lshlrev_b32_e32 v100, 16, v144
	v_mfma_f32_16x16x32_bf16 v[134:137], v[208:211], v[52:55], v[134:137]
	v_mul_f32_e64 v210, v104, v100
	v_mul_f32_e64 v211, v105, v101
	v_mov_b32_e32 v100, v127
	v_mov_b32_e32 v101, v129
	v_pk_add_f32 v[100:101], v[166:167], v[100:101]
	v_and_b32_e32 v105, 0xffff0000, v149
	v_and_b32_e32 v104, 0xffff0000, v148
	v_mov_b32_e32 v127, v128
	v_pk_mul_f32 v[208:209], v[100:101], v[104:105]
	v_pk_add_f32 v[100:101], v[166:167], v[126:127]
	v_lshlrev_b32_e32 v97, 16, v149
	v_lshlrev_b32_e32 v96, 16, v148
	v_mfma_f32_16x16x32_bf16 v[114:117], v[204:207], v[76:79], v[114:117]
	v_mul_f32_e64 v206, v100, v96
	v_mul_f32_e64 v207, v101, v97
	v_mov_b32_e32 v96, v131
	v_mov_b32_e32 v97, v133
	v_pk_add_f32 v[96:97], v[168:169], v[96:97]
	v_and_b32_e32 v101, 0xffff0000, v153
	v_and_b32_e32 v100, 0xffff0000, v152
	v_mov_b32_e32 v131, v132
	v_pk_mul_f32 v[204:205], v[96:97], v[100:101]
	v_pk_add_f32 v[96:97], v[168:169], v[130:131]
	v_lshlrev_b32_e32 v93, 16, v153
	v_lshlrev_b32_e32 v92, 16, v152
	v_pk_mul_f32 v[202:203], v[96:97], v[92:93]
	v_mov_b32_e32 v92, v135
	v_mov_b32_e32 v93, v137
	v_pk_add_f32 v[92:93], v[170:171], v[92:93]
	v_and_b32_e32 v97, 0xffff0000, v157
	v_and_b32_e32 v96, 0xffff0000, v156
	v_mov_b32_e32 v135, v136
	v_pk_mul_f32 v[216:217], v[138:139], v[200:201]
	v_pk_mul_f32 v[200:201], v[92:93], v[96:97]
	v_pk_add_f32 v[92:93], v[170:171], v[134:135]
	v_lshlrev_b32_e32 v89, 16, v157
	v_lshlrev_b32_e32 v88, 16, v156
	v_pk_mul_f32 v[104:105], v[92:93], v[88:89]
	v_mov_b32_e32 v88, v223
	v_mov_b32_e32 v89, v225
	v_pk_add_f32 v[88:89], v[172:173], v[88:89]
	v_and_b32_e32 v93, 0xffff0000, v239
	v_and_b32_e32 v92, 0xffff0000, v238
	v_mov_b32_e32 v223, v224
	v_pk_mul_f32 v[100:101], v[88:89], v[92:93]
	v_pk_add_f32 v[88:89], v[172:173], v[222:223]
	v_lshlrev_b32_e32 v85, 16, v239
	v_lshlrev_b32_e32 v84, 16, v238
	v_pk_mul_f32 v[96:97], v[88:89], v[84:85]
	v_mov_b32_e32 v84, v227
	v_mov_b32_e32 v85, v229
	v_pk_add_f32 v[84:85], v[174:175], v[84:85]
	v_and_b32_e32 v89, 0xffff0000, v249
	v_and_b32_e32 v88, 0xffff0000, v248
	v_mov_b32_e32 v227, v228
	v_pk_mul_f32 v[92:93], v[84:85], v[88:89]
	v_pk_add_f32 v[84:85], v[174:175], v[226:227]
	v_lshlrev_b32_e32 v81, 16, v249
	v_lshlrev_b32_e32 v80, 16, v248
	v_pk_mul_f32 v[80:81], v[84:85], v[80:81]
	v_mov_b32_e32 v84, v115
	v_mov_b32_e32 v85, v117
	v_pk_add_f32 v[84:85], v[176:177], v[84:85]
	v_and_b32_e32 v89, 0xffff0000, v161
	v_and_b32_e32 v88, 0xffff0000, v160
	v_mov_b32_e32 v115, v116
	v_pk_mul_f32 v[88:89], v[84:85], v[88:89]
	v_pk_add_f32 v[84:85], v[176:177], v[114:115]
	ds_read_b64_tr_b16 v[114:115], v220 offset:352
	ds_read_b64_tr_b16 v[234:235], v220 offset:2592
	ds_read_b64_tr_b16 v[236:237], v220 offset:2912
	s_waitcnt lgkmcnt(2)
	v_mfma_f32_16x16x32_bf16 v[120:123], v[112:115], v[16:19], 0
	v_lshlrev_b32_e32 v109, 16, v161
	v_lshlrev_b32_e32 v108, 16, v160
	v_pk_mul_f32 v[84:85], v[84:85], v[108:109]
	v_mfma_f32_16x16x32_bf16 v[226:229], v[112:115], v[48:51], 0
	v_bfe_u32 v196, v216, 16, 1
	v_add3_u32 v196, v216, v196, s68
	v_bfe_u32 v195, v217, 16, 1
	v_mfma_f32_16x16x32_bf16 v[230:233], v[112:115], v[32:35], 0
	v_add3_u32 v195, v217, v195, s68
	v_mfma_f32_16x16x32_bf16 v[116:119], v[112:115], v[8:11], 0
	v_mfma_f32_16x16x32_bf16 v[124:127], v[112:115], v[24:27], 0
	v_mfma_f32_16x16x32_bf16 v[222:225], v[112:115], v[0:3], 0
	v_mfma_f32_16x16x32_bf16 v[132:135], v[112:115], v[4:7], 0
	v_mfma_f32_16x16x32_bf16 v[112:115], v[112:115], v[40:43], 0
	s_nop 5
	v_mov_b32_e32 v108, v223
	v_mov_b32_e32 v223, v224
	v_mov_b32_e32 v109, v225
	s_waitcnt lgkmcnt(0)
	v_mfma_f32_16x16x32_bf16 v[128:131], v[234:237], v[20:23], v[120:123]
	v_add_f32_e64 v222, v162, v222
	v_add_f32_e64 v223, v163, v223
	v_pk_add_f32 v[108:109], v[162:163], v[108:109]
	v_mfma_f32_16x16x32_bf16 v[120:123], v[234:237], v[56:59], v[226:229]
	v_mfma_f32_16x16x32_bf16 v[226:229], v[234:237], v[36:39], v[230:233]
	s_nop 2
	ds_read_b64_tr_b16 v[230:231], v220 offset:5152
	ds_read_b64_tr_b16 v[232:233], v220 offset:5472
	v_mfma_f32_16x16x32_bf16 v[136:139], v[234:237], v[12:15], v[116:119]
	v_mfma_f32_16x16x32_bf16 v[116:119], v[234:237], v[28:31], v[124:127]
	v_mfma_f32_16x16x32_bf16 v[112:115], v[234:237], v[44:47], v[112:115]
	s_waitcnt lgkmcnt(0)
	v_mfma_f32_16x16x32_bf16 v[124:127], v[230:233], v[52:55], v[116:119]
	v_mfma_f32_16x16x32_bf16 v[116:119], v[230:233], v[64:67], v[226:229]
	s_nop 2
	ds_read_b64_tr_b16 v[226:227], v220 offset:7712
	ds_read_b64_tr_b16 v[228:229], v220 offset:8032
	v_mfma_f32_16x16x32_bf16 v[112:115], v[230:233], v[72:75], v[112:115]
	s_waitcnt lgkmcnt(0)
; #define LAS __attribute__((address_space(3)))
; #define MFMA16(a, b, c) __builtin_amdgcn_mfma_f32_16x16x32_bf16((a), (b), (c), 0, 0, 0)
; __device__ __forceinline__ unsigned pk2(float lo, float hi) { return f2bf(lo) | (f2bf(hi) << 16); }
; __device__ __forceinline__ float bflo(unsigned w) { return __uint_as_float(w << 16); }
; __device__ __forceinline__ float bfhi(unsigned w) { return __uint_as_float(w & 0xffff0000u); }
; __device__ __forceinline__ void sgu_item(LAS unsigned char* wl, const bf16* proj, bf16* ymix, const float* vstat, const float* sgu_g, const bf16* Wm, const float* sgu_b, int chunk, int h, int lane) {
;     ...
;         for (int n = 0; n < 2; ++n) {
;             f32x4 z[8];
; #pragma unroll
;             for (int tb = 0; tb < 8; ++tb) z[tb] = (f32x4){0.f, 0.f, 0.f, 0.f};
;             int f = 0;
; #pragma unroll
;             for (int ks = 0; ks < 4; ++ks) {
;                 LAS unsigned char* ad = wl + (ks * 32 + 8 * q + (r >> 2)) * VP2 + (16 * n) * 2 + 8 * (r & 3);
;                 const s16x4 lo = __builtin_bit_cast(s16x4, __builtin_amdgcn_ds_read_tr16_b64_v4i16((LAS s16x4*)ad));
;                 const s16x4 hi = __builtin_bit_cast(s16x4, __builtin_amdgcn_ds_read_tr16_b64_v4i16((LAS s16x4*)(ad + 4 * VP2)));
;                 const bf16x8 vf = __builtin_shufflevector(lo, hi, 0, 1, 2, 3, 4, 5, 6, 7);
; #pragma unroll
;                 for (int tb = 2 * ks; tb < 8; ++tb) z[tb] = MFMA16(vf, wmf[f++], z[tb]);
;             }
; #pragma unroll
;             for (int tb = 0; tb < 8; ++tb) { const v4u uu = uu8[tb]; const unsigned ux = n == 0 ? uu.x : uu.z, uy = n == 0 ? uu.y : uu.w;
;                 v2u o; o.x = pk2(bflo(ux) * (z[tb][0] + bias[tb]), bfhi(ux) * (z[tb][1] + bias[tb])); o.y = pk2(bflo(uy) * (z[tb][2] + bias[tb]), bfhi(uy) * (z[tb][3] + bias[tb]));
;                 if (n == 0) olo[tb] = o;
;                 else { v4u w; w.x = olo[tb].x; w.y = olo[tb].y; w.z = o.x; w.w = o.y; *(v4u*)(ymix + (R0 + 16 * tb + r) * D + 512 + colv + 8 * q) = w; } }
	v_mfma_f32_16x16x32_bf16 v[116:119], v[226:229], v[68:71], v[116:119]
	v_mfma_f32_16x16x32_bf16 v[112:115], v[226:229], v[76:79], v[112:115]
	v_and_b32_e32 v227, 0xffff0000, v143
	v_and_b32_e32 v226, 0xffff0000, v142
	v_lshlrev_b32_e32 v107, 16, v143
	v_lshlrev_b32_e32 v106, 16, v142
	v_pk_mul_f32 v[106:107], v[222:223], v[106:107]
	v_pk_mul_f32 v[108:109], v[108:109], v[226:227]
	v_bfe_u32 v197, v106, 16, 1
	v_bfe_u32 v216, v107, 16, 1
	v_bfe_u32 v192, v109, 16, 1
	v_bfe_u32 v194, v108, 16, 1
	v_add3_u32 v107, v107, v216, s68
	v_add3_u32 v106, v106, v197, s68
	v_add3_u32 v108, v108, v194, s68
	v_add3_u32 v109, v109, v192, s68
	v_bfe_u32 v192, v214, 16, 1
	v_bfe_u32 v194, v215, 16, 1
	v_lshrrev_b32_e32 v106, 16, v106
	v_lshrrev_b32_e32 v107, 16, v107
	v_add3_u32 v194, v215, v194, s68
	v_add3_u32 v192, v214, v192, s68
	v_and_or_b32 v217, v109, s37, v107
	v_and_or_b32 v216, v108, s37, v106
	v_lshl_add_u64 v[106:107], v[182:183], 0, s[20:21]
	v_lshrrev_b32_e32 v192, 16, v192
	v_lshrrev_b32_e32 v194, 16, v194
	v_add_co_u32_e32 v108, vcc, s0, v106
	v_and_or_b32 v215, v195, s37, v194
	v_and_or_b32 v214, v196, s37, v192
	v_addc_co_u32_e32 v109, vcc, 0, v107, vcc
	global_store_dwordx4 v[108:109], v[214:217], off offset:1024
	v_mov_b32_e32 v108, v133
	v_mov_b32_e32 v109, v135
	v_mov_b32_e32 v133, v134
	v_pk_add_f32 v[108:109], v[164:165], v[108:109]
	v_and_b32_e32 v215, 0xffff0000, v147
	v_and_b32_e32 v214, 0xffff0000, v146
	v_pk_add_f32 v[132:133], v[164:165], v[132:133]
	v_lshlrev_b32_e32 v103, 16, v147
	v_lshlrev_b32_e32 v102, 16, v146
	v_pk_mul_f32 v[108:109], v[108:109], v[214:215]
	v_pk_mul_f32 v[102:103], v[132:133], v[102:103]
	v_bfe_u32 v134, v213, 16, 1
	v_bfe_u32 v132, v109, 16, 1
	v_bfe_u32 v133, v108, 16, 1
	v_bfe_u32 v135, v212, 16, 1
	v_add3_u32 v194, v213, v134, s68
	v_bfe_u32 v134, v102, 16, 1
	v_add3_u32 v192, v212, v135, s68
	v_add3_u32 v108, v108, v133, s68
	v_add3_u32 v109, v109, v132, s68
	v_bfe_u32 v132, v210, 16, 1
	v_bfe_u32 v133, v211, 16, 1
	v_bfe_u32 v135, v103, 16, 1
	v_add3_u32 v102, v102, v134, s68
	v_add3_u32 v103, v103, v135, s68
	v_add3_u32 v133, v211, v133, s68
	v_add3_u32 v132, v210, v132, s68
	v_lshrrev_b32_e32 v102, 16, v102
	s_mov_b32 s0, 0x10908000
	v_lshrrev_b32_e32 v132, 16, v132
	v_lshrrev_b32_e32 v133, 16, v133
	v_lshrrev_b32_e32 v103, 16, v103
	v_and_or_b32 v134, v108, s37, v102
	v_add_co_u32_e32 v102, vcc, s0, v106
	v_and_or_b32 v135, v109, s37, v103
	v_and_or_b32 v133, v194, s37, v133
	v_and_or_b32 v132, v192, s37, v132
	v_addc_co_u32_e32 v103, vcc, 0, v107, vcc
	global_store_dwordx4 v[102:103], v[132:135], off offset:1024
	v_mov_b32_e32 v102, v137
	v_mov_b32_e32 v103, v139
	v_pk_add_f32 v[102:103], v[166:167], v[102:103]
	v_and_b32_e32 v109, 0xffff0000, v151
	v_and_b32_e32 v108, 0xffff0000, v150
	v_mov_b32_e32 v137, v138
	v_pk_mul_f32 v[102:103], v[102:103], v[108:109]
	v_pk_add_f32 v[108:109], v[166:167], v[136:137]
	v_lshlrev_b32_e32 v99, 16, v151
	v_lshlrev_b32_e32 v98, 16, v150
	v_pk_mul_f32 v[98:99], v[108:109], v[98:99]
	v_bfe_u32 v133, v208, 16, 1
	v_bfe_u32 v108, v103, 16, 1
	v_bfe_u32 v109, v102, 16, 1
	v_add3_u32 v136, v208, v133, s68
	v_bfe_u32 v133, v98, 16, 1
	v_add3_u32 v102, v102, v109, s68
	v_add3_u32 v103, v103, v108, s68
	v_bfe_u32 v108, v206, 16, 1
	v_bfe_u32 v109, v207, 16, 1
	v_bfe_u32 v134, v99, 16, 1
	v_add3_u32 v98, v98, v133, s68
	v_bfe_u32 v132, v209, 16, 1
	v_add3_u32 v99, v99, v134, s68
	v_add3_u32 v109, v207, v109, s68
	v_add3_u32 v108, v206, v108, s68
	v_lshrrev_b32_e32 v98, 16, v98
	s_mov_b32 s0, 0x10910000
	v_add3_u32 v132, v209, v132, s68
	v_lshrrev_b32_e32 v108, 16, v108
	v_lshrrev_b32_e32 v109, 16, v109
	v_lshrrev_b32_e32 v99, 16, v99
	v_and_or_b32 v134, v102, s37, v98
	v_add_co_u32_e32 v98, vcc, s0, v106
	v_and_or_b32 v135, v103, s37, v99
	v_and_or_b32 v133, v132, s37, v109
	v_and_or_b32 v132, v136, s37, v108
	v_addc_co_u32_e32 v99, vcc, 0, v107, vcc
	global_store_dwordx4 v[98:99], v[132:135], off offset:1024
	v_mov_b32_e32 v98, v129
	v_mov_b32_e32 v99, v131
	v_pk_add_f32 v[98:99], v[168:169], v[98:99]
	v_and_b32_e32 v103, 0xffff0000, v155
	v_and_b32_e32 v102, 0xffff0000, v154
	v_mov_b32_e32 v129, v130
	v_pk_mul_f32 v[98:99], v[98:99], v[102:103]
	v_pk_add_f32 v[102:103], v[168:169], v[128:129]
	v_lshlrev_b32_e32 v95, 16, v155
	v_lshlrev_b32_e32 v94, 16, v154
	v_pk_mul_f32 v[94:95], v[102:103], v[94:95]
	v_bfe_u32 v102, v99, 16, 1
	v_bfe_u32 v103, v98, 16, 1
	v_add3_u32 v98, v98, v103, s68
	v_add3_u32 v99, v99, v102, s68
	v_bfe_u32 v102, v202, 16, 1
	v_bfe_u32 v103, v203, 16, 1
	v_bfe_u32 v128, v94, 16, 1
	v_bfe_u32 v129, v95, 16, 1
	v_bfe_u32 v108, v205, 16, 1
	v_bfe_u32 v109, v204, 16, 1
	v_add3_u32 v95, v95, v129, s68
	v_add3_u32 v94, v94, v128, s68
	v_add3_u32 v103, v203, v103, s68
	v_add3_u32 v102, v202, v102, s68
	v_add3_u32 v109, v204, v109, s68
	v_add3_u32 v108, v205, v108, s68
	v_lshrrev_b32_e32 v102, 16, v102
	v_lshrrev_b32_e32 v103, 16, v103
	v_lshrrev_b32_e32 v94, 16, v94
	v_lshrrev_b32_e32 v95, 16, v95
	v_and_or_b32 v131, v99, s37, v95
	v_and_or_b32 v130, v98, s37, v94
	v_and_or_b32 v129, v108, s37, v103
	v_and_or_b32 v128, v109, s37, v102
	v_lshl_add_u64 v[94:95], v[184:185], 0, s[20:21]
	global_store_dwordx4 v[94:95], v[128:131], off
	v_mov_b32_e32 v94, v125
	v_mov_b32_e32 v95, v127
	v_pk_add_f32 v[94:95], v[170:171], v[94:95]
; __device__ __forceinline__ unsigned pk2(float lo, float hi) { return f2bf(lo) | (f2bf(hi) << 16); }
; __device__ __forceinline__ float bflo(unsigned w) { return __uint_as_float(w << 16); }
; __device__ __forceinline__ float bfhi(unsigned w) { return __uint_as_float(w & 0xffff0000u); }
; #define LDS_WAIT() asm volatile("s_waitcnt lgkmcnt(0)" ::: "memory")
; __device__ __forceinline__ void sgu_item(LAS unsigned char* wl, const bf16* proj, bf16* ymix, const float* vstat, const float* sgu_g, const bf16* Wm, const float* sgu_b, int chunk, int h, int lane) {
;     ...
;             for (int tb = 0; tb < 8; ++tb) { const v4u uu = uu8[tb]; const unsigned ux = n == 0 ? uu.x : uu.z, uy = n == 0 ? uu.y : uu.w;
;                 v2u o; o.x = pk2(bflo(ux) * (z[tb][0] + bias[tb]), bfhi(ux) * (z[tb][1] + bias[tb])); o.y = pk2(bflo(uy) * (z[tb][2] + bias[tb]), bfhi(uy) * (z[tb][3] + bias[tb]));
;                 if (n == 0) olo[tb] = o;
;                 else { v4u w; w.x = olo[tb].x; w.y = olo[tb].y; w.z = o.x; w.w = o.y; *(v4u*)(ymix + (R0 + 16 * tb + r) * D + 512 + colv + 8 * q) = w; } }
;         }
;         LDS_WAIT();
	v_and_b32_e32 v99, 0xffff0000, v159
	v_and_b32_e32 v98, 0xffff0000, v158
	v_mov_b32_e32 v125, v126
	v_pk_mul_f32 v[94:95], v[94:95], v[98:99]
	v_pk_add_f32 v[98:99], v[170:171], v[124:125]
	v_lshlrev_b32_e32 v91, 16, v159
	v_lshlrev_b32_e32 v90, 16, v158
	v_pk_mul_f32 v[90:91], v[98:99], v[90:91]
	v_bfe_u32 v103, v200, 16, 1
	v_bfe_u32 v98, v95, 16, 1
	v_bfe_u32 v99, v94, 16, 1
	v_add3_u32 v108, v200, v103, s68
	v_bfe_u32 v103, v90, 16, 1
	v_mfma_f32_16x16x32_bf16 v[120:123], v[230:233], v[60:63], v[120:123]
	v_add3_u32 v94, v94, v99, s68
	v_add3_u32 v95, v95, v98, s68
	v_bfe_u32 v98, v104, 16, 1
	v_bfe_u32 v99, v105, 16, 1
	v_bfe_u32 v109, v91, 16, 1
	v_add3_u32 v90, v90, v103, s68
	v_bfe_u32 v102, v201, 16, 1
	v_add3_u32 v91, v91, v109, s68
	v_add3_u32 v99, v105, v99, s68
	v_add3_u32 v98, v104, v98, s68
	v_lshrrev_b32_e32 v90, 16, v90
	s_mov_b32 s0, 0x10920000
	v_add3_u32 v102, v201, v102, s68
	v_lshrrev_b32_e32 v98, 16, v98
	v_lshrrev_b32_e32 v99, 16, v99
	v_lshrrev_b32_e32 v91, 16, v91
	v_and_or_b32 v104, v94, s37, v90
	v_add_co_u32_e32 v90, vcc, s0, v106
	v_and_or_b32 v105, v95, s37, v91
	v_and_or_b32 v103, v102, s37, v99
	v_and_or_b32 v102, v108, s37, v98
	v_addc_co_u32_e32 v91, vcc, 0, v107, vcc
	global_store_dwordx4 v[90:91], v[102:105], off offset:1024
	v_mov_b32_e32 v90, v121
	v_mov_b32_e32 v91, v123
	v_pk_add_f32 v[90:91], v[172:173], v[90:91]
	v_and_b32_e32 v95, 0xffff0000, v241
	v_and_b32_e32 v94, 0xffff0000, v240
	v_mov_b32_e32 v121, v122
	v_pk_mul_f32 v[90:91], v[90:91], v[94:95]
	v_pk_add_f32 v[94:95], v[172:173], v[120:121]
	v_lshlrev_b32_e32 v87, 16, v241
	v_lshlrev_b32_e32 v86, 16, v240
	v_pk_mul_f32 v[86:87], v[94:95], v[86:87]
	v_bfe_u32 v99, v100, 16, 1
	v_bfe_u32 v94, v91, 16, 1
	v_bfe_u32 v95, v90, 16, 1
	v_bfe_u32 v98, v101, 16, 1
	v_add3_u32 v99, v100, v99, s68
	v_bfe_u32 v100, v86, 16, 1
	v_add3_u32 v98, v101, v98, s68
	v_add3_u32 v90, v90, v95, s68
	v_add3_u32 v91, v91, v94, s68
	v_bfe_u32 v94, v96, 16, 1
	v_bfe_u32 v95, v97, 16, 1
	v_bfe_u32 v101, v87, 16, 1
	v_add3_u32 v86, v86, v100, s68
	v_add3_u32 v87, v87, v101, s68
	v_add3_u32 v95, v97, v95, s68
	v_add3_u32 v94, v96, v94, s68
	v_lshrrev_b32_e32 v86, 16, v86
	s_mov_b32 s0, 0x10928000
	v_lshrrev_b32_e32 v94, 16, v94
	v_lshrrev_b32_e32 v95, 16, v95
	v_lshrrev_b32_e32 v87, 16, v87
	v_and_or_b32 v96, v90, s37, v86
	v_add_co_u32_e32 v86, vcc, s0, v106
	v_and_or_b32 v97, v91, s37, v87
	v_and_or_b32 v95, v98, s37, v95
	v_and_or_b32 v94, v99, s37, v94
	v_addc_co_u32_e32 v87, vcc, 0, v107, vcc
	global_store_dwordx4 v[86:87], v[94:97], off offset:1024
	v_mov_b32_e32 v86, v117
	v_mov_b32_e32 v87, v119
	v_pk_add_f32 v[86:87], v[174:175], v[86:87]
	v_and_b32_e32 v91, 0xffff0000, v251
	v_and_b32_e32 v90, 0xffff0000, v250
	v_mov_b32_e32 v117, v118
	v_pk_mul_f32 v[86:87], v[86:87], v[90:91]
	v_pk_add_f32 v[90:91], v[174:175], v[116:117]
	v_lshlrev_b32_e32 v83, 16, v251
	v_lshlrev_b32_e32 v82, 16, v250
	v_pk_mul_f32 v[82:83], v[90:91], v[82:83]
	v_bfe_u32 v94, v93, 16, 1
	v_bfe_u32 v90, v87, 16, 1
	v_bfe_u32 v91, v86, 16, 1
	v_bfe_u32 v95, v92, 16, 1
	v_add3_u32 v93, v93, v94, s68
	v_bfe_u32 v94, v82, 16, 1
	v_add3_u32 v92, v92, v95, s68
	v_add3_u32 v86, v86, v91, s68
	v_add3_u32 v87, v87, v90, s68
	v_bfe_u32 v90, v80, 16, 1
	v_bfe_u32 v91, v81, 16, 1
	v_bfe_u32 v95, v83, 16, 1
	v_add3_u32 v82, v82, v94, s68
	v_add3_u32 v83, v83, v95, s68
	v_add3_u32 v81, v81, v91, s68
	v_add3_u32 v80, v80, v90, s68
	v_lshrrev_b32_e32 v82, 16, v82
	s_mov_b32 s0, 0x10930000
	v_lshrrev_b32_e32 v80, 16, v80
	v_lshrrev_b32_e32 v81, 16, v81
	v_lshrrev_b32_e32 v83, 16, v83
	v_and_or_b32 v82, v86, s37, v82
	v_add_co_u32_e32 v86, vcc, s0, v106
	v_and_or_b32 v83, v87, s37, v83
	v_and_or_b32 v81, v93, s37, v81
	v_and_or_b32 v80, v92, s37, v80
	v_addc_co_u32_e32 v87, vcc, 0, v107, vcc
	global_store_dwordx4 v[86:87], v[80:83], off offset:1024
	v_lshlrev_b32_e32 v87, 16, v243
	v_lshlrev_b32_e32 v86, 16, v242
	v_mov_b32_e32 v80, v113
	v_mov_b32_e32 v81, v115
	v_pk_add_f32 v[80:81], v[176:177], v[80:81]
	v_and_b32_e32 v83, 0xffff0000, v243
	v_and_b32_e32 v82, 0xffff0000, v242
	v_mov_b32_e32 v113, v114
	v_pk_mul_f32 v[80:81], v[80:81], v[82:83]
	v_pk_add_f32 v[82:83], v[176:177], v[112:113]
	v_bfe_u32 v90, v89, 16, 1
	v_pk_mul_f32 v[82:83], v[82:83], v[86:87]
	v_bfe_u32 v86, v81, 16, 1
	v_bfe_u32 v87, v80, 16, 1
	v_bfe_u32 v91, v88, 16, 1
	v_add3_u32 v88, v88, v91, s68
	v_add3_u32 v89, v89, v90, s68
	v_add3_u32 v80, v80, v87, s68
	v_add3_u32 v81, v81, v86, s68
	v_bfe_u32 v86, v84, 16, 1
	v_bfe_u32 v87, v85, 16, 1
	v_bfe_u32 v90, v82, 16, 1
	v_bfe_u32 v91, v83, 16, 1
	v_add3_u32 v83, v83, v91, s68
	v_add3_u32 v82, v82, v90, s68
	v_add3_u32 v85, v85, v87, s68
	v_add3_u32 v84, v84, v86, s68
	v_lshrrev_b32_e32 v84, 16, v84
	v_lshrrev_b32_e32 v85, 16, v85
	v_lshrrev_b32_e32 v82, 16, v82
	v_lshrrev_b32_e32 v83, 16, v83
	v_and_or_b32 v83, v81, s37, v83
	v_and_or_b32 v82, v80, s37, v82
	v_and_or_b32 v81, v89, s37, v85
	v_and_or_b32 v80, v88, s37, v84
	v_lshl_add_u64 v[84:85], v[180:181], 0, s[20:21]
	global_store_dwordx4 v[84:85], v[80:83], off
	s_waitcnt lgkmcnt(0)
	s_add_u32 s20, s20, 64
	s_addc_u32 s21, s21, 0
	s_cmpk_lg_i32 s20, 0x100
	s_cbranch_scc1 .LBB0_511
	s_add_i32 s5, s5, s77
	s_add_i32 s4, s4, s7
	s_cmp_lt_i32 s5, s2
	s_cbranch_scc1 .LBB0_510
